# scan loop: back-edge register rotation and its wait moved in front of the chunk barrier
# speedup vs baseline: 1.0040x; 1.0032x over previous
; #define LAS __attribute__((address_space(3)))
; DI bf16x8 pack8(const f32x4& a, const f32x4& b) { u32x4 p; p.x = pk2(a[0], a[1]); p.y = pk2(a[2], a[3]); p.z = pk2(b[0], b[1]); p.w = pk2(b[2], b[3]); return __builtin_bit_cast(bf16x8, p); }
; #define MFMA16(a, b, c) __builtin_amdgcn_mfma_f32_16x16x32_bf16((a), (b), (c), 0, 0, 0)
; DI void scan_phase(LAS unsigned char* lds, const Args& a, int l) {
;     ...
;             for (int ks = 0; ks < 4; ++ks)
; #pragma unroll
;                 for (int m = 0; m < 4; ++m) { const bf16x8 av = *(const LAS bf16x8*)(B + O_WK + (16 * m + fr) * 272 + (32 * ks + 8 * fq) * 2); ws[m] = MFMA16(av, Sb[ks], ws[m]); }
; #pragma unroll
;             for (int ks = 0; ks < 4; ++ks)
; #pragma unroll
;                 for (int m = 0; m < 4; ++m) { const bf16x8 av = *(const LAS bf16x8*)(B + O_QD + (16 * m + fr) * 272 + (32 * ks + 8 * fq) * 2); o[m] = MFMA16(av, Sb[ks], o[m]); }
;             f32x4 u[4];
; #pragma unroll
;             for (int m = 0; m < 4; ++m) u[m] = uvc[m] - ws[m];
;             bf16x8 Ub[2]; Ub[0] = pack8(u[0], u[1]); Ub[1] = pack8(u[2], u[3]);
; #pragma unroll
;             for (int ks = 0; ks < 2; ++ks)
; #pragma unroll
;                 for (int m = 0; m < 4; ++m) { const bf16x8 av = *(const LAS bf16x8*)(B + O_QK + (16 * m + fr) * 144 + (32 * ks + 8 * fq) * 2); o[m] = MFMA16(av, Ub[ks], o[m]); }
; #pragma unroll
;             for (int mt = 0; mt < 8; ++mt) S[mt] = S[mt] * gec;
.LBB0_110:
	ds_read_b128 v[242:245], v250 offset:13120
	s_waitcnt lgkmcnt(7)
	v_mfma_f32_16x16x32_bf16 v[182:185], v[214:217], v[88:91], 0
	v_mul_f32_e32 v0, v150, v0
	v_mul_f32_e32 v1, v150, v1
	ds_read_b128 v[214:217], v250 offset:128
	s_waitcnt lgkmcnt(7)
	v_mfma_f32_16x16x32_bf16 v[186:189], v[218:221], v[88:91], 0
	v_mul_f32_e32 v2, v150, v2
	v_mul_f32_e32 v3, v150, v3
	s_mov_b64 s[10:11], 0x4000
	v_lshl_add_u64 v[146:147], v[146:147], 0, s[10:11]
	ds_read_b128 v[218:221], v250 offset:4480
	s_waitcnt lgkmcnt(7)
	v_mfma_f32_16x16x32_bf16 v[190:193], v[222:225], v[88:91], 0
	v_mul_f32_e32 v4, v150, v4
	v_mul_f32_e32 v5, v150, v5
	ds_read_b128 v[222:225], v250 offset:8832
	s_waitcnt lgkmcnt(7)
	v_mfma_f32_16x16x32_bf16 v[194:197], v[226:229], v[88:91], 0
	v_mul_f32_e32 v6, v150, v6
	v_mul_f32_e32 v7, v150, v7
	s_add_u32 s17, s17, 4
	s_addc_u32 s28, s28, 0
	ds_read_b128 v[226:229], v250 offset:13184
	s_waitcnt lgkmcnt(7)
	v_mfma_f32_16x16x32_bf16 v[182:185], v[230:233], v[84:87], v[182:185]
	v_mul_f32_e32 v8, v150, v8
	v_mul_f32_e32 v9, v150, v9
	ds_read_b128 v[230:233], v250 offset:192
	s_waitcnt lgkmcnt(7)
	v_mfma_f32_16x16x32_bf16 v[186:189], v[234:237], v[84:87], v[186:189]
	v_mul_f32_e32 v10, v150, v10
	v_mul_f32_e32 v11, v150, v11
	v_lshl_add_u64 v[144:145], v[144:145], 0, s[26:27]
	ds_read_b128 v[234:237], v250 offset:4544
	s_waitcnt lgkmcnt(7)
	v_mfma_f32_16x16x32_bf16 v[190:193], v[238:241], v[84:87], v[190:193]
	v_mul_f32_e32 v12, v150, v12
	v_mul_f32_e32 v13, v150, v13
	ds_read_b128 v[238:241], v250 offset:8896
	s_waitcnt lgkmcnt(7)
	v_mfma_f32_16x16x32_bf16 v[194:197], v[242:245], v[84:87], v[194:197]
	v_mul_f32_e32 v14, v150, v14
	v_mul_f32_e32 v15, v150, v15
	s_mov_b64 s[10:11], 0x8000
	v_lshl_add_u64 v[148:149], v[148:149], 0, s[10:11]
	ds_read_b128 v[242:245], v250 offset:13248
	s_waitcnt lgkmcnt(7)
	v_mfma_f32_16x16x32_bf16 v[182:185], v[214:217], v[80:83], v[182:185]
	v_mul_f32_e32 v16, v150, v16
	v_mul_f32_e32 v17, v150, v17
	ds_read_b128 v[214:217], v250 offset:17408
	s_waitcnt lgkmcnt(7)
	v_mfma_f32_16x16x32_bf16 v[186:189], v[218:221], v[80:83], v[186:189]
	v_mul_f32_e32 v18, v150, v18
	v_mul_f32_e32 v19, v150, v19
	ds_read_b128 v[218:221], v250 offset:21760
	s_waitcnt lgkmcnt(7)
	v_mfma_f32_16x16x32_bf16 v[190:193], v[222:225], v[80:83], v[190:193]
	v_mul_f32_e32 v20, v150, v20
	v_mul_f32_e32 v21, v150, v21
	ds_read_b128 v[222:225], v250 offset:26112
	s_waitcnt lgkmcnt(7)
	v_mfma_f32_16x16x32_bf16 v[194:197], v[226:229], v[80:83], v[194:197]
	v_mul_f32_e32 v22, v150, v22
	v_mul_f32_e32 v23, v150, v23
	ds_read_b128 v[226:229], v250 offset:30464
	s_waitcnt lgkmcnt(7)
	v_mfma_f32_16x16x32_bf16 v[182:185], v[230:233], v[76:79], v[182:185]
	v_mul_f32_e32 v24, v150, v24
	v_mul_f32_e32 v25, v150, v25
	ds_read_b128 v[230:233], v250 offset:17472
	s_waitcnt lgkmcnt(7)
	v_mfma_f32_16x16x32_bf16 v[186:189], v[234:237], v[76:79], v[186:189]
	v_mul_f32_e32 v26, v150, v26
	v_mul_f32_e32 v27, v150, v27
	ds_read_b128 v[234:237], v250 offset:21824
	s_waitcnt lgkmcnt(7)
	v_mfma_f32_16x16x32_bf16 v[190:193], v[238:241], v[76:79], v[190:193]
	v_mul_f32_e32 v28, v150, v28
	v_mul_f32_e32 v29, v150, v29
	ds_read_b128 v[238:241], v250 offset:26176
	s_waitcnt lgkmcnt(7)
	v_mfma_f32_16x16x32_bf16 v[194:197], v[242:245], v[76:79], v[194:197]
	v_mul_f32_e32 v30, v150, v30
	v_mul_f32_e32 v31, v150, v31
	ds_read_b128 v[242:245], v250 offset:30528
	s_waitcnt lgkmcnt(7)
	v_mfma_f32_16x16x32_bf16 v[198:201], v[214:217], v[88:91], 0
	ds_read_b128 v[214:217], v250 offset:17536
	s_waitcnt lgkmcnt(7)
	v_mfma_f32_16x16x32_bf16 v[202:205], v[218:221], v[88:91], 0
	v_sub_f32_e32 v182, v104, v182
	v_sub_f32_e32 v183, v105, v183
	v_sub_f32_e32 v184, v106, v184
	v_sub_f32_e32 v185, v107, v185
	ds_read_b128 v[218:221], v250 offset:21888
	s_waitcnt lgkmcnt(7)
	v_mfma_f32_16x16x32_bf16 v[206:209], v[222:225], v[88:91], 0
	v_sub_f32_e32 v186, v96, v186
	v_sub_f32_e32 v187, v97, v187
	v_sub_f32_e32 v188, v98, v188
	v_sub_f32_e32 v189, v99, v189
	ds_read_b128 v[222:225], v250 offset:26240
	s_waitcnt lgkmcnt(7)
	v_mfma_f32_16x16x32_bf16 v[210:213], v[226:229], v[88:91], 0
	v_sub_f32_e32 v190, v92, v190
	v_sub_f32_e32 v191, v93, v191
	v_sub_f32_e32 v192, v94, v192
	v_sub_f32_e32 v193, v95, v193
	ds_read_b128 v[226:229], v250 offset:30592
	s_waitcnt lgkmcnt(7)
	v_mfma_f32_16x16x32_bf16 v[198:201], v[230:233], v[84:87], v[198:201]
	v_sub_f32_e32 v194, v100, v194
	v_sub_f32_e32 v195, v101, v195
	v_sub_f32_e32 v196, v102, v196
	v_sub_f32_e32 v197, v103, v197
	ds_read_b128 v[230:233], v250 offset:17600
	s_waitcnt lgkmcnt(7)
	v_mfma_f32_16x16x32_bf16 v[202:205], v[234:237], v[84:87], v[202:205]
	v_cvt_pk_bf16_f32 v246, v182, v183
	v_cvt_pk_bf16_f32 v247, v184, v185
	ds_read_b128 v[234:237], v250 offset:21952
	s_waitcnt lgkmcnt(7)
	v_mfma_f32_16x16x32_bf16 v[206:209], v[238:241], v[84:87], v[206:209]
	v_cvt_pk_bf16_f32 v248, v186, v187
	v_cvt_pk_bf16_f32 v249, v188, v189
	ds_read_b128 v[238:241], v250 offset:26304
	s_waitcnt lgkmcnt(7)
	v_mfma_f32_16x16x32_bf16 v[210:213], v[242:245], v[84:87], v[210:213]
	v_cvt_pk_bf16_f32 v182, v190, v191
	v_cvt_pk_bf16_f32 v183, v192, v193
	ds_read_b128 v[242:245], v250 offset:30656
	s_waitcnt lgkmcnt(7)
	v_mfma_f32_16x16x32_bf16 v[198:201], v[214:217], v[80:83], v[198:201]
	v_cvt_pk_bf16_f32 v184, v194, v195
	v_cvt_pk_bf16_f32 v185, v196, v197
	ds_read_b128 v[214:217], v251 offset:34816
	s_waitcnt lgkmcnt(7)
	v_mfma_f32_16x16x32_bf16 v[202:205], v[218:221], v[80:83], v[202:205]
	ds_read_b128 v[218:221], v251 offset:39424
	s_waitcnt lgkmcnt(7)
	v_mfma_f32_16x16x32_bf16 v[206:209], v[222:225], v[80:83], v[206:209]
	ds_read_b128 v[222:225], v251 offset:44032
	s_waitcnt lgkmcnt(7)
; #define LAS __attribute__((address_space(3)))
; DI bf16x8 pack8(const f32x4& a, const f32x4& b) { u32x4 p; p.x = pk2(a[0], a[1]); p.y = pk2(a[2], a[3]); p.z = pk2(b[0], b[1]); p.w = pk2(b[2], b[3]); return __builtin_bit_cast(bf16x8, p); }
; #define MFMA16(a, b, c) __builtin_amdgcn_mfma_f32_16x16x32_bf16((a), (b), (c), 0, 0, 0)
; DI void scan_phase(LAS unsigned char* lds, const Args& a, int l) {
;     ...
;                 for (int m = 0; m < 4; ++m) { const bf16x8 av = *(const LAS bf16x8*)(B + O_QK + (16 * m + fr) * 144 + (32 * ks + 8 * fq) * 2); o[m] = MFMA16(av, Ub[ks], o[m]); }
; #pragma unroll
;             for (int mt = 0; mt < 8; ++mt) S[mt] = S[mt] * gec;
; #pragma unroll
;             for (int ks = 0; ks < 2; ++ks)
; #pragma unroll
;                 for (int mt = 0; mt < 8; ++mt) { const bf16x8 av = *(const LAS bf16x8*)(B + O_KET + (16 * mt + fr) * 144 + (32 * ks + 8 * fq) * 2); S[mt] = MFMA16(av, Ub[ks], S[mt]); }
; #pragma unroll
;             for (int ks = 0; ks < 4; ++ks) Sb[ks] = pack8(S[2 * ks], S[2 * ks + 1]);
;             float* op = O + (size_t)(b * 2048 + n * 64 + 4 * fq) * 512 + h * 128 + 16 * s + fr;
; #pragma unroll
;             for (int m = 0; m < 4; ++m)
; #pragma unroll
;                 for (int reg = 0; reg < 4; ++reg) op[(size_t)(16 * m + reg) * 512] = o[m][reg];
; #pragma unroll
;             for (int m = 0; m < 4; ++m) uvc[m] = uvn[m];
;             gec = gen;
;             __syncthreads();
;         }
	v_mfma_f32_16x16x32_bf16 v[210:213], v[226:229], v[80:83], v[210:213]
	ds_read_b128 v[226:229], v251 offset:48640
	s_waitcnt lgkmcnt(7)
	v_mfma_f32_16x16x32_bf16 v[198:201], v[230:233], v[76:79], v[198:201]
	ds_read_b128 v[230:233], v251 offset:34960
	s_waitcnt lgkmcnt(7)
	v_mfma_f32_16x16x32_bf16 v[202:205], v[234:237], v[76:79], v[202:205]
	ds_read_b128 v[234:237], v251 offset:39568
	s_waitcnt lgkmcnt(7)
	v_mfma_f32_16x16x32_bf16 v[206:209], v[238:241], v[76:79], v[206:209]
	ds_read_b128 v[238:241], v251 offset:44176
	s_waitcnt lgkmcnt(7)
	v_mfma_f32_16x16x32_bf16 v[210:213], v[242:245], v[76:79], v[210:213]
	ds_read_b128 v[242:245], v251 offset:48784
	s_waitcnt lgkmcnt(7)
	v_mfma_f32_16x16x32_bf16 v[0:3], v[214:217], v[246:249], v[0:3]
	ds_read_b128 v[214:217], v251 offset:34880
	s_waitcnt lgkmcnt(7)
	v_mfma_f32_16x16x32_bf16 v[4:7], v[218:221], v[246:249], v[4:7]
	ds_read_b128 v[218:221], v251 offset:39488
	s_waitcnt lgkmcnt(7)
	v_mfma_f32_16x16x32_bf16 v[8:11], v[222:225], v[246:249], v[8:11]
	v_ashrrev_i32_e32 v143, 31, v142
	ds_read_b128 v[222:225], v251 offset:44096
	s_waitcnt lgkmcnt(7)
	v_mfma_f32_16x16x32_bf16 v[12:15], v[226:229], v[246:249], v[12:15]
	ds_read_b128 v[226:229], v251 offset:48704
	s_waitcnt lgkmcnt(7)
	v_mfma_f32_16x16x32_bf16 v[16:19], v[230:233], v[246:249], v[16:19]
	v_lshlrev_b64 v[162:163], 11, v[142:143]
	ds_read_b128 v[230:233], v251 offset:35024
	s_waitcnt lgkmcnt(7)
	v_mfma_f32_16x16x32_bf16 v[20:23], v[234:237], v[246:249], v[20:23]
	ds_read_b128 v[234:237], v251 offset:39632
	s_waitcnt lgkmcnt(7)
	v_mfma_f32_16x16x32_bf16 v[24:27], v[238:241], v[246:249], v[24:27]
	v_lshl_add_u64 v[162:163], v[140:141], 0, v[162:163]
	ds_read_b128 v[238:241], v251 offset:44240
	s_waitcnt lgkmcnt(7)
	v_mfma_f32_16x16x32_bf16 v[28:31], v[242:245], v[246:249], v[28:31]
	ds_read_b128 v[242:245], v251 offset:48848
	s_waitcnt lgkmcnt(7)
	v_mfma_f32_16x16x32_bf16 v[0:3], v[214:217], v[182:185], v[0:3]
	v_add_u32_e32 v142, 64, v142
	ds_read_b128 v[214:217], v251 offset:53248
	s_waitcnt lgkmcnt(7)
	v_mfma_f32_16x16x32_bf16 v[4:7], v[218:221], v[182:185], v[4:7]
	ds_read_b128 v[218:221], v251 offset:57856
	s_waitcnt lgkmcnt(7)
	v_mfma_f32_16x16x32_bf16 v[8:11], v[222:225], v[182:185], v[8:11]
	ds_read_b128 v[222:225], v251 offset:53392
	s_waitcnt lgkmcnt(7)
	v_mfma_f32_16x16x32_bf16 v[12:15], v[226:229], v[182:185], v[12:15]
	ds_read_b128 v[226:229], v251 offset:58000
	s_waitcnt lgkmcnt(7)
	v_mfma_f32_16x16x32_bf16 v[16:19], v[230:233], v[182:185], v[16:19]
	ds_read_b128 v[230:233], v251 offset:53312
	s_waitcnt lgkmcnt(7)
	v_mfma_f32_16x16x32_bf16 v[20:23], v[234:237], v[182:185], v[20:23]
	v_cvt_pk_bf16_f32 v88, v0, v1
	v_cvt_pk_bf16_f32 v89, v2, v3
	v_cvt_pk_bf16_f32 v90, v4, v5
	v_cvt_pk_bf16_f32 v91, v6, v7
	ds_read_b128 v[234:237], v251 offset:57920
	s_waitcnt lgkmcnt(7)
	v_mfma_f32_16x16x32_bf16 v[24:27], v[238:241], v[182:185], v[24:27]
	ds_read_b128 v[238:241], v251 offset:53456
	s_waitcnt lgkmcnt(7)
	v_mfma_f32_16x16x32_bf16 v[28:31], v[242:245], v[182:185], v[28:31]
	v_cvt_pk_bf16_f32 v84, v8, v9
	v_cvt_pk_bf16_f32 v85, v10, v11
	v_cvt_pk_bf16_f32 v86, v12, v13
	v_cvt_pk_bf16_f32 v87, v14, v15
	ds_read_b128 v[242:245], v251 offset:58064
	s_waitcnt lgkmcnt(7)
	v_mfma_f32_16x16x32_bf16 v[198:201], v[214:217], v[246:249], v[198:201]
	s_waitcnt lgkmcnt(6)
	v_mfma_f32_16x16x32_bf16 v[202:205], v[218:221], v[246:249], v[202:205]
	s_waitcnt lgkmcnt(5)
	v_mfma_f32_16x16x32_bf16 v[206:209], v[222:225], v[246:249], v[206:209]
	v_cvt_pk_bf16_f32 v80, v16, v17
	v_cvt_pk_bf16_f32 v81, v18, v19
	v_cvt_pk_bf16_f32 v82, v20, v21
	v_cvt_pk_bf16_f32 v83, v22, v23
	s_waitcnt lgkmcnt(4)
	v_mfma_f32_16x16x32_bf16 v[210:213], v[226:229], v[246:249], v[210:213]
	s_waitcnt lgkmcnt(3)
	v_mfma_f32_16x16x32_bf16 v[198:201], v[230:233], v[182:185], v[198:201]
	s_waitcnt lgkmcnt(2)
	v_mfma_f32_16x16x32_bf16 v[202:205], v[234:237], v[182:185], v[202:205]
	v_cvt_pk_bf16_f32 v76, v24, v25
	v_cvt_pk_bf16_f32 v77, v26, v27
	v_cvt_pk_bf16_f32 v78, v28, v29
	v_cvt_pk_bf16_f32 v79, v30, v31
	s_waitcnt lgkmcnt(1)
	v_mfma_f32_16x16x32_bf16 v[206:209], v[238:241], v[182:185], v[206:209]
	s_waitcnt lgkmcnt(0)
	v_mfma_f32_16x16x32_bf16 v[210:213], v[242:245], v[182:185], v[210:213]
	s_mov_b64 s[10:11], 0x1000
	v_lshl_add_u64 v[214:215], v[162:163], 0, s[10:11]
	s_mov_b64 s[10:11], 0x9000
	v_lshl_add_u64 v[216:217], v[162:163], 0, s[10:11]
	s_mov_b64 s[10:11], 0x11000
	v_lshl_add_u64 v[218:219], v[162:163], 0, s[10:11]
	s_mov_b64 s[10:11], 0x19000
	v_lshl_add_u64 v[220:221], v[162:163], 0, s[10:11]
	s_add_i32 s9, s9, 1
	global_store_dword v[214:215], v198, off offset:-4096
	global_store_dword v[214:215], v199, off offset:-2048
	global_store_dword v[214:215], v200, off
	global_store_dword v[214:215], v201, off offset:2048
	global_store_dword v[216:217], v202, off offset:-4096
	global_store_dword v[216:217], v203, off offset:-2048
	global_store_dword v[216:217], v204, off
	global_store_dword v[216:217], v205, off offset:2048
	global_store_dword v[218:219], v206, off offset:-4096
	global_store_dword v[218:219], v207, off offset:-2048
	global_store_dword v[218:219], v208, off
	global_store_dword v[218:219], v209, off offset:2048
	global_store_dword v[220:221], v210, off offset:-4096
	global_store_dword v[220:221], v211, off offset:-2048
	global_store_dword v[220:221], v212, off
	global_store_dword v[220:221], v213, off offset:2048
	s_waitcnt vmcnt(16)
	v_mov_b64_e32 v[102:103], v[34:35]
	v_mov_b64_e32 v[94:95], v[38:39]
	v_mov_b64_e32 v[98:99], v[42:43]
	v_mov_b64_e32 v[106:107], v[46:47]
	v_mov_b64_e32 v[100:101], v[32:33]
	v_mov_b64_e32 v[92:93], v[36:37]
	v_mov_b64_e32 v[96:97], v[40:41]
	v_mov_b64_e32 v[104:105], v[44:45]
	v_mov_b32_e32 v150, v128
	s_cmp_eq_u32 s9, 32
	s_barrier
	s_cbranch_scc1 .LBB0_106
	s_branch .LBB0_108
